# prologue de-serialisation (row phase, layers 1-4): first row's loads issued before the conditioning-vector loads, and the two conditioning round trips merged into one wait
# speedup vs baseline: 1.0073x; 1.0011x over previous
.LBB0_425:
	s_add_i32 s0, s60, 0xfffff000
	s_ashr_i32 s0, s0, 10
	s_add_i32 s0, s0, 1
	s_cmpk_gt_i32 s60, 0xfff
	s_waitcnt vmcnt(0)
	v_cndmask_b32_e64 v0, 0, 1, s[4:5]
	s_cselect_b32 s34, s0, 0
	v_cmp_ne_u32_e64 s[38:39], 1, v0
	s_andn2_b64 vcc, exec, s[4:5]
	s_waitcnt lgkmcnt(0)
	s_barrier
	s_and_b64 vcc, exec, s[14:15]
	s_cbranch_vccz .Lrows_noearly
	v_mad_i64_i32 v[160:161], s[0:1], v41, s70, v[42:43]
	global_load_dwordx2 v[128:129], v[160:161], off nt
	global_load_dwordx2 v[130:131], v[160:161], off offset:512 nt
	global_load_dwordx2 v[132:133], v[160:161], off offset:1024 nt
	global_load_dwordx2 v[134:135], v[160:161], off offset:1536 nt
	global_load_dwordx2 v[136:137], v[160:161], off offset:2048 nt
	global_load_dwordx2 v[138:139], v[160:161], off offset:2560 nt
	global_load_dwordx2 v[140:141], v[160:161], off offset:3072 nt
	global_load_dwordx2 v[142:143], v[160:161], off offset:3584 nt
	v_mad_i64_i32 v[120:121], s[0:1], v41, s70, v[62:63]
	global_load_dwordx2 v[104:105], v[120:121], off nt
	global_load_dwordx2 v[106:107], v[120:121], off offset:512 nt
	global_load_dwordx2 v[108:109], v[120:121], off offset:1024 nt
	global_load_dwordx2 v[110:111], v[120:121], off offset:1536 nt
	global_load_dwordx2 v[112:113], v[120:121], off offset:2048 nt
	global_load_dwordx2 v[114:115], v[120:121], off offset:2560 nt
	global_load_dwordx2 v[116:117], v[120:121], off offset:3072 nt
	global_load_dwordx2 v[118:119], v[120:121], off offset:3584 nt
.Lrows_noearly:
	s_andn2_b64 vcc, exec, s[4:5]
	s_cbranch_vccnz .LBB0_427
	s_add_i32 s0, s34, s59
	s_mulk_i32 s0, 0x1800
	s_ashr_i32 s1, s0, 31
	s_lshl_b64 s[0:1], s[0:1], 2
	v_readlane_b32 s35, v252, 20
	s_add_u32 s0, s35, s0
	v_readlane_b32 s35, v252, 21
	s_addc_u32 s1, s35, s1
	v_lshl_add_u64 v[0:1], v[36:37], 2, s[0:1]
	v_add_co_u32_e32 v4, vcc, 0x4000, v0
	s_nop 1
	v_addc_co_u32_e32 v5, vcc, 0, v1, vcc
	global_load_dwordx4 v[148:151], v[54:55], off
	global_load_dwordx4 v[152:155], v[4:5], off

.LBB0_433:
	s_andn2_b64 vcc, exec, s[4:5]
	s_cbranch_vccnz .Lrows_noa
	s_waitcnt vmcnt(0)
	v_pk_mul_f32 v[150:151], v[154:155], v[150:151]
	v_pk_mul_f32 v[148:149], v[152:153], v[148:149]
	ds_write_b128 v39, v[148:151]

.LBB0_435:
	v_add_u32_e32 v66, s61, v41
	s_mov_b64 s[0:1], -1
	s_and_b64 vcc, exec, s[14:15]
	s_cbranch_vccz .LBB0_438
	s_cmp_lg_u32 s61, 0
	s_cbranch_scc1 .Lrows_issue
	v_mov_b64_e32 v[2:3], v[128:129]
	v_mov_b64_e32 v[4:5], v[130:131]
	v_mov_b64_e32 v[6:7], v[132:133]
	v_mov_b64_e32 v[8:9], v[134:135]
	v_mov_b64_e32 v[10:11], v[136:137]
	v_mov_b64_e32 v[32:33], v[138:139]
	v_mov_b64_e32 v[34:35], v[140:141]
	v_mov_b64_e32 v[68:69], v[142:143]
	s_branch .Lrows_unpack
.Lrows_issue:
	v_mad_i64_i32 v[0:1], s[0:1], v66, s70, v[42:43]
	global_load_dwordx2 v[2:3], v[0:1], off nt
	global_load_dwordx2 v[4:5], v[0:1], off offset:512 nt
	global_load_dwordx2 v[6:7], v[0:1], off offset:1024 nt
	global_load_dwordx2 v[8:9], v[0:1], off offset:1536 nt
	global_load_dwordx2 v[10:11], v[0:1], off offset:2048 nt
	global_load_dwordx2 v[32:33], v[0:1], off offset:2560 nt
	global_load_dwordx2 v[34:35], v[0:1], off offset:3072 nt
	global_load_dwordx2 v[68:69], v[0:1], off offset:3584 nt
	v_mad_i64_i32 v[120:121], s[0:1], v66, s70, v[62:63]
	global_load_dwordx2 v[104:105], v[120:121], off nt
	global_load_dwordx2 v[106:107], v[120:121], off offset:512 nt
	global_load_dwordx2 v[108:109], v[120:121], off offset:1024 nt
	global_load_dwordx2 v[110:111], v[120:121], off offset:1536 nt
	global_load_dwordx2 v[112:113], v[120:121], off offset:2048 nt
	global_load_dwordx2 v[114:115], v[120:121], off offset:2560 nt
	global_load_dwordx2 v[116:117], v[120:121], off offset:3072 nt
	global_load_dwordx2 v[118:119], v[120:121], off offset:3584 nt
.Lrows_unpack:
	s_waitcnt vmcnt(15)
	v_lshlrev_b32_e32 v28, 16, v2
	v_and_b32_e32 v29, 0xffff0000, v2
	v_lshlrev_b32_e32 v30, 16, v3
	v_and_b32_e32 v31, 0xffff0000, v3
	s_waitcnt vmcnt(14)
	v_lshlrev_b32_e32 v24, 16, v4
	v_and_b32_e32 v25, 0xffff0000, v4
	v_lshlrev_b32_e32 v26, 16, v5
	v_and_b32_e32 v27, 0xffff0000, v5
	s_waitcnt vmcnt(13)
	v_lshlrev_b32_e32 v20, 16, v6
	v_and_b32_e32 v21, 0xffff0000, v6
	v_lshlrev_b32_e32 v22, 16, v7
	v_and_b32_e32 v23, 0xffff0000, v7
	s_waitcnt vmcnt(12)
	v_lshlrev_b32_e32 v16, 16, v8
	v_and_b32_e32 v17, 0xffff0000, v8
	v_lshlrev_b32_e32 v18, 16, v9
	v_and_b32_e32 v19, 0xffff0000, v9
	s_waitcnt vmcnt(11)
	v_lshlrev_b32_e32 v12, 16, v10
	v_and_b32_e32 v13, 0xffff0000, v10
	v_lshlrev_b32_e32 v14, 16, v11
	v_and_b32_e32 v15, 0xffff0000, v11
	s_waitcnt vmcnt(10)
	v_lshlrev_b32_e32 v8, 16, v32
	v_and_b32_e32 v9, 0xffff0000, v32
	v_lshlrev_b32_e32 v10, 16, v33
	v_and_b32_e32 v11, 0xffff0000, v33
	s_waitcnt vmcnt(9)
	v_lshlrev_b32_e32 v4, 16, v34
	v_and_b32_e32 v5, 0xffff0000, v34
	v_lshlrev_b32_e32 v6, 16, v35
	v_and_b32_e32 v7, 0xffff0000, v35
	s_waitcnt vmcnt(8)
	v_lshlrev_b32_e32 v0, 16, v68
	v_and_b32_e32 v1, 0xffff0000, v68
	v_lshlrev_b32_e32 v2, 16, v69
	v_and_b32_e32 v3, 0xffff0000, v69
	v_ashrrev_i32_e32 v67, 31, v66
	s_branch .Lrows_o_loaded
